# v33 + recurrence: next-token operand reads issued before the per-step wait (counted lgkmcnt)
# baseline (speedup 1.0000x reference)
.LBB0_1238:
	s_or_b64 exec, exec, s[18:19]
	s_waitcnt lgkmcnt(0)
	s_barrier
	s_cmp_lg_u32 s100, 0
	s_cselect_b32 s97, 0x800, 0
	v_add_u32_e32 v167, s97, v114
	ds_read_b128 v[72:75], v114 offset:41216
	ds_read_b128 v[68:71], v114 offset:45312
	ds_read_b128 v[64:67], v114 offset:49408
	ds_read_b128 v[56:59], v114 offset:53504
	ds_read_b128 v[60:63], v167 offset:28928
	ds_read2st64_b32 v[214:215], v115 offset1:1
	ds_read_b128 v[134:137], v114 offset:41344
	ds_read_b128 v[138:141], v114 offset:45440
	ds_read_b128 v[142:145], v114 offset:49536
	ds_read_b128 v[130:133], v167 offset:29056
	s_waitcnt lgkmcnt(4)
	v_dot2_f32_f16 v151, v127, v72, 0
	v_dot2_f32_f16 v151, v126, v73, v151
	v_dot2_f32_f16 v151, v125, v74, v151
	v_dot2_f32_f16 v151, v124, v75, v151
	v_pk_mul_f16 v153, v214, v64
	v_pk_mul_f16 v154, v214, v65
	v_pk_mul_f16 v155, v214, v66
	v_add_f32_dpp v151, v151, v151 quad_perm:[1,0,3,2] row_mask:0xf bank_mask:0xf bound_ctrl:1
	v_pk_mul_f16 v156, v214, v67
	s_nop 0
	v_add_f32_dpp v151, v151, v151 quad_perm:[2,3,0,1] row_mask:0xf bank_mask:0xf bound_ctrl:1
	s_nop 1
	v_add_f32_dpp v151, v151, v151 row_half_mirror row_mask:0xf bank_mask:0xf bound_ctrl:1
	v_cvt_pkrtz_f16_f32 v152, -v151, -v151
	ds_read_b128 v[146:149], v114 offset:53632
	v_pk_fma_f16 v153, v152, v68, v153
	v_pk_fma_f16 v154, v152, v69, v154
	v_pk_fma_f16 v155, v152, v70, v155
	v_pk_fma_f16 v156, v152, v71, v156
	v_pk_fma_f16 v127, v127, v60, v153
	v_pk_fma_f16 v126, v126, v61, v154
	v_pk_fma_f16 v125, v125, v62, v155
	v_pk_fma_f16 v124, v124, v63, v156
	ds_read_b128 v[72:75], v114 offset:41472
	ds_read_b128 v[68:71], v114 offset:45568
	ds_read_b128 v[64:67], v114 offset:49664
	ds_read_b128 v[60:63], v167 offset:29184
	ds_read2st64_b32 v[216:217], v115 offset0:2 offset1:3
	s_waitcnt lgkmcnt(6)
	v_dot2_f32_f16 v151, v127, v134, 0
	v_dot2_f32_f16 v151, v126, v135, v151
	v_dot2_f32_f16 v151, v125, v136, v151
	v_dot2_f32_f16 v151, v124, v137, v151
	v_dot2_f32_f16 v157, v127, v56, 0
	v_dot2_f32_f16 v157, v126, v57, v157
	v_dot2_f32_f16 v157, v125, v58, v157
	v_add_f32_dpp v151, v151, v151 quad_perm:[1,0,3,2] row_mask:0xf bank_mask:0xf bound_ctrl:1
	v_dot2_f32_f16 v157, v124, v59, v157
	v_pk_mul_f16 v153, v215, v142
	v_add_f32_dpp v151, v151, v151 quad_perm:[2,3,0,1] row_mask:0xf bank_mask:0xf bound_ctrl:1
	v_pk_mul_f16 v154, v215, v143
	v_pk_mul_f16 v155, v215, v144
	v_pk_mul_f16 v156, v215, v145
	v_add_f32_dpp v151, v151, v151 row_half_mirror row_mask:0xf bank_mask:0xf bound_ctrl:1
	v_cvt_pkrtz_f16_f32 v152, -v151, -v151
	ds_read_b128 v[56:59], v114 offset:53760
	v_pk_fma_f16 v153, v152, v138, v153
	v_pk_fma_f16 v154, v152, v139, v154
	v_pk_fma_f16 v155, v152, v140, v155
	v_pk_fma_f16 v156, v152, v141, v156
	v_pk_fma_f16 v127, v127, v130, v153
	v_pk_fma_f16 v126, v126, v131, v154
	v_pk_fma_f16 v125, v125, v132, v155
	v_pk_fma_f16 v124, v124, v133, v156
	ds_read_b128 v[134:137], v114 offset:41600
	ds_read_b128 v[138:141], v114 offset:45696
	ds_read_b128 v[142:145], v114 offset:49792
	ds_read_b128 v[130:133], v167 offset:29312
	s_waitcnt lgkmcnt(5)
	v_dot2_f32_f16 v151, v127, v72, 0
	v_dot2_f32_f16 v151, v126, v73, v151
	v_dot2_f32_f16 v151, v125, v74, v151
	v_dot2_f32_f16 v151, v124, v75, v151
	v_dot2_f32_f16 v158, v127, v146, 0
	v_dot2_f32_f16 v158, v126, v147, v158
	v_dot2_f32_f16 v158, v125, v148, v158
	v_add_f32_dpp v151, v151, v151 quad_perm:[1,0,3,2] row_mask:0xf bank_mask:0xf bound_ctrl:1
	v_dot2_f32_f16 v158, v124, v149, v158
	v_pk_mul_f16 v153, v216, v64
	v_add_f32_dpp v151, v151, v151 quad_perm:[2,3,0,1] row_mask:0xf bank_mask:0xf bound_ctrl:1
	v_pk_mul_f16 v154, v216, v65
	v_pk_mul_f16 v155, v216, v66
	v_pk_mul_f16 v156, v216, v67
	v_add_f32_dpp v151, v151, v151 row_half_mirror row_mask:0xf bank_mask:0xf bound_ctrl:1
	v_cvt_pkrtz_f16_f32 v152, -v151, -v151
	ds_read_b128 v[146:149], v114 offset:53888
	ds_write2st64_b32 v116, v157, v158 offset0:0 offset1:8
	v_pk_fma_f16 v153, v152, v68, v153
	v_pk_fma_f16 v154, v152, v69, v154
	v_pk_fma_f16 v155, v152, v70, v155
	v_pk_fma_f16 v156, v152, v71, v156
	v_pk_fma_f16 v127, v127, v60, v153
	v_pk_fma_f16 v126, v126, v61, v154
	v_pk_fma_f16 v125, v125, v62, v155
	v_pk_fma_f16 v124, v124, v63, v156
	ds_read_b128 v[72:75], v114 offset:41728
	ds_read_b128 v[68:71], v114 offset:45824
	ds_read_b128 v[64:67], v114 offset:49920
	ds_read_b128 v[60:63], v167 offset:29440
	ds_read2st64_b32 v[214:215], v115 offset0:4 offset1:5
	s_waitcnt lgkmcnt(7)
	v_dot2_f32_f16 v151, v127, v134, 0
	v_dot2_f32_f16 v151, v126, v135, v151
	v_dot2_f32_f16 v151, v125, v136, v151
	v_dot2_f32_f16 v151, v124, v137, v151
	v_dot2_f32_f16 v157, v127, v56, 0
	v_dot2_f32_f16 v157, v126, v57, v157
	v_dot2_f32_f16 v157, v125, v58, v157
	v_add_f32_dpp v151, v151, v151 quad_perm:[1,0,3,2] row_mask:0xf bank_mask:0xf bound_ctrl:1
	v_dot2_f32_f16 v157, v124, v59, v157
	v_pk_mul_f16 v153, v217, v142
	v_add_f32_dpp v151, v151, v151 quad_perm:[2,3,0,1] row_mask:0xf bank_mask:0xf bound_ctrl:1
	v_pk_mul_f16 v154, v217, v143
	v_pk_mul_f16 v155, v217, v144
	v_pk_mul_f16 v156, v217, v145
	v_add_f32_dpp v151, v151, v151 row_half_mirror row_mask:0xf bank_mask:0xf bound_ctrl:1
	v_cvt_pkrtz_f16_f32 v152, -v151, -v151
	ds_read_b128 v[56:59], v114 offset:54016
	v_pk_fma_f16 v153, v152, v138, v153
	v_pk_fma_f16 v154, v152, v139, v154
	v_pk_fma_f16 v155, v152, v140, v155
	v_pk_fma_f16 v156, v152, v141, v156
	v_pk_fma_f16 v127, v127, v130, v153
	v_pk_fma_f16 v126, v126, v131, v154
	v_pk_fma_f16 v125, v125, v132, v155
	v_pk_fma_f16 v124, v124, v133, v156
	ds_read_b128 v[134:137], v114 offset:41856
	ds_read_b128 v[138:141], v114 offset:45952
	ds_read_b128 v[142:145], v114 offset:50048
	ds_read_b128 v[130:133], v167 offset:29568
	s_waitcnt lgkmcnt(5)
	v_dot2_f32_f16 v151, v127, v72, 0
	v_dot2_f32_f16 v151, v126, v73, v151
	v_dot2_f32_f16 v151, v125, v74, v151
	v_dot2_f32_f16 v151, v124, v75, v151
	v_dot2_f32_f16 v158, v127, v146, 0
	v_dot2_f32_f16 v158, v126, v147, v158
	v_dot2_f32_f16 v158, v125, v148, v158
	v_add_f32_dpp v151, v151, v151 quad_perm:[1,0,3,2] row_mask:0xf bank_mask:0xf bound_ctrl:1
	v_dot2_f32_f16 v158, v124, v149, v158
	v_pk_mul_f16 v153, v214, v64
	v_add_f32_dpp v151, v151, v151 quad_perm:[2,3,0,1] row_mask:0xf bank_mask:0xf bound_ctrl:1
	v_pk_mul_f16 v154, v214, v65
	v_pk_mul_f16 v155, v214, v66
	v_pk_mul_f16 v156, v214, v67
	v_add_f32_dpp v151, v151, v151 row_half_mirror row_mask:0xf bank_mask:0xf bound_ctrl:1
	v_cvt_pkrtz_f16_f32 v152, -v151, -v151
	ds_read_b128 v[146:149], v114 offset:54144
	ds_write2st64_b32 v116, v157, v158 offset0:16 offset1:24
	v_pk_fma_f16 v153, v152, v68, v153
	v_pk_fma_f16 v154, v152, v69, v154
	v_pk_fma_f16 v155, v152, v70, v155
	v_pk_fma_f16 v156, v152, v71, v156
	v_pk_fma_f16 v127, v127, v60, v153
	v_pk_fma_f16 v126, v126, v61, v154
	v_pk_fma_f16 v125, v125, v62, v155
	v_pk_fma_f16 v124, v124, v63, v156
	ds_read_b128 v[72:75], v114 offset:41984
	ds_read_b128 v[68:71], v114 offset:46080
	ds_read_b128 v[64:67], v114 offset:50176
	ds_read_b128 v[60:63], v167 offset:29696
	ds_read2st64_b32 v[216:217], v115 offset0:6 offset1:7
	s_waitcnt lgkmcnt(7)
	v_dot2_f32_f16 v151, v127, v134, 0
	v_dot2_f32_f16 v151, v126, v135, v151
	v_dot2_f32_f16 v151, v125, v136, v151
	v_dot2_f32_f16 v151, v124, v137, v151
	v_dot2_f32_f16 v157, v127, v56, 0
	v_dot2_f32_f16 v157, v126, v57, v157
	v_dot2_f32_f16 v157, v125, v58, v157
	v_add_f32_dpp v151, v151, v151 quad_perm:[1,0,3,2] row_mask:0xf bank_mask:0xf bound_ctrl:1
	v_dot2_f32_f16 v157, v124, v59, v157
	v_pk_mul_f16 v153, v215, v142
	v_add_f32_dpp v151, v151, v151 quad_perm:[2,3,0,1] row_mask:0xf bank_mask:0xf bound_ctrl:1
	v_pk_mul_f16 v154, v215, v143
	v_pk_mul_f16 v155, v215, v144
	v_pk_mul_f16 v156, v215, v145
	v_add_f32_dpp v151, v151, v151 row_half_mirror row_mask:0xf bank_mask:0xf bound_ctrl:1
	v_cvt_pkrtz_f16_f32 v152, -v151, -v151
	ds_read_b128 v[56:59], v114 offset:54272
	v_pk_fma_f16 v153, v152, v138, v153
	v_pk_fma_f16 v154, v152, v139, v154
	v_pk_fma_f16 v155, v152, v140, v155
	v_pk_fma_f16 v156, v152, v141, v156
	v_pk_fma_f16 v127, v127, v130, v153
	v_pk_fma_f16 v126, v126, v131, v154
	v_pk_fma_f16 v125, v125, v132, v155
	v_pk_fma_f16 v124, v124, v133, v156
	ds_read_b128 v[134:137], v114 offset:42112
	ds_read_b128 v[138:141], v114 offset:46208
	ds_read_b128 v[142:145], v114 offset:50304
	ds_read_b128 v[130:133], v167 offset:29824
	s_waitcnt lgkmcnt(5)
	v_dot2_f32_f16 v151, v127, v72, 0
	v_dot2_f32_f16 v151, v126, v73, v151
	v_dot2_f32_f16 v151, v125, v74, v151
	v_dot2_f32_f16 v151, v124, v75, v151
	v_dot2_f32_f16 v158, v127, v146, 0
	v_dot2_f32_f16 v158, v126, v147, v158
	v_dot2_f32_f16 v158, v125, v148, v158
	v_add_f32_dpp v151, v151, v151 quad_perm:[1,0,3,2] row_mask:0xf bank_mask:0xf bound_ctrl:1
	v_dot2_f32_f16 v158, v124, v149, v158
	v_pk_mul_f16 v153, v216, v64
	v_add_f32_dpp v151, v151, v151 quad_perm:[2,3,0,1] row_mask:0xf bank_mask:0xf bound_ctrl:1
	v_pk_mul_f16 v154, v216, v65
	v_pk_mul_f16 v155, v216, v66
	v_pk_mul_f16 v156, v216, v67
	v_add_f32_dpp v151, v151, v151 row_half_mirror row_mask:0xf bank_mask:0xf bound_ctrl:1
	v_cvt_pkrtz_f16_f32 v152, -v151, -v151
	ds_read_b128 v[146:149], v114 offset:54400
	ds_write2st64_b32 v116, v157, v158 offset0:32 offset1:40
	v_pk_fma_f16 v153, v152, v68, v153
	v_pk_fma_f16 v154, v152, v69, v154
	v_pk_fma_f16 v155, v152, v70, v155
	v_pk_fma_f16 v156, v152, v71, v156
	v_pk_fma_f16 v127, v127, v60, v153
	v_pk_fma_f16 v126, v126, v61, v154
	v_pk_fma_f16 v125, v125, v62, v155
	v_pk_fma_f16 v124, v124, v63, v156
	ds_read_b128 v[72:75], v114 offset:42240
	ds_read_b128 v[68:71], v114 offset:46336
	ds_read_b128 v[64:67], v114 offset:50432
	ds_read_b128 v[60:63], v167 offset:29952
	ds_read2st64_b32 v[214:215], v115 offset0:8 offset1:9
	s_waitcnt lgkmcnt(7)
	v_dot2_f32_f16 v151, v127, v134, 0
	v_dot2_f32_f16 v151, v126, v135, v151
	v_dot2_f32_f16 v151, v125, v136, v151
	v_dot2_f32_f16 v151, v124, v137, v151
	v_dot2_f32_f16 v157, v127, v56, 0
	v_dot2_f32_f16 v157, v126, v57, v157
	v_dot2_f32_f16 v157, v125, v58, v157
	v_add_f32_dpp v151, v151, v151 quad_perm:[1,0,3,2] row_mask:0xf bank_mask:0xf bound_ctrl:1
	v_dot2_f32_f16 v157, v124, v59, v157
	v_pk_mul_f16 v153, v217, v142
	v_add_f32_dpp v151, v151, v151 quad_perm:[2,3,0,1] row_mask:0xf bank_mask:0xf bound_ctrl:1
	v_pk_mul_f16 v154, v217, v143
	v_pk_mul_f16 v155, v217, v144
	v_pk_mul_f16 v156, v217, v145
	v_add_f32_dpp v151, v151, v151 row_half_mirror row_mask:0xf bank_mask:0xf bound_ctrl:1
	v_cvt_pkrtz_f16_f32 v152, -v151, -v151
	ds_read_b128 v[56:59], v114 offset:54528
	v_pk_fma_f16 v153, v152, v138, v153
	v_pk_fma_f16 v154, v152, v139, v154
	v_pk_fma_f16 v155, v152, v140, v155
	v_pk_fma_f16 v156, v152, v141, v156
	v_pk_fma_f16 v127, v127, v130, v153
	v_pk_fma_f16 v126, v126, v131, v154
	v_pk_fma_f16 v125, v125, v132, v155
	v_pk_fma_f16 v124, v124, v133, v156
	ds_read_b128 v[134:137], v114 offset:42368
	ds_read_b128 v[138:141], v114 offset:46464
	ds_read_b128 v[142:145], v114 offset:50560
	ds_read_b128 v[130:133], v167 offset:30080
	s_waitcnt lgkmcnt(5)
	v_dot2_f32_f16 v151, v127, v72, 0
	v_dot2_f32_f16 v151, v126, v73, v151
	v_dot2_f32_f16 v151, v125, v74, v151
	v_dot2_f32_f16 v151, v124, v75, v151
	v_dot2_f32_f16 v158, v127, v146, 0
	v_dot2_f32_f16 v158, v126, v147, v158
	v_dot2_f32_f16 v158, v125, v148, v158
	v_add_f32_dpp v151, v151, v151 quad_perm:[1,0,3,2] row_mask:0xf bank_mask:0xf bound_ctrl:1
	v_dot2_f32_f16 v158, v124, v149, v158
	v_pk_mul_f16 v153, v214, v64
	v_add_f32_dpp v151, v151, v151 quad_perm:[2,3,0,1] row_mask:0xf bank_mask:0xf bound_ctrl:1
	v_pk_mul_f16 v154, v214, v65
	v_pk_mul_f16 v155, v214, v66
	v_pk_mul_f16 v156, v214, v67
	v_add_f32_dpp v151, v151, v151 row_half_mirror row_mask:0xf bank_mask:0xf bound_ctrl:1
	v_cvt_pkrtz_f16_f32 v152, -v151, -v151
	ds_read_b128 v[146:149], v114 offset:54656
	ds_write2st64_b32 v116, v157, v158 offset0:48 offset1:56
	v_pk_fma_f16 v153, v152, v68, v153
	v_pk_fma_f16 v154, v152, v69, v154
	v_pk_fma_f16 v155, v152, v70, v155
	v_pk_fma_f16 v156, v152, v71, v156
	v_pk_fma_f16 v127, v127, v60, v153
	v_pk_fma_f16 v126, v126, v61, v154
	v_pk_fma_f16 v125, v125, v62, v155
	v_pk_fma_f16 v124, v124, v63, v156
	ds_read_b128 v[72:75], v114 offset:42496
	ds_read_b128 v[68:71], v114 offset:46592
	ds_read_b128 v[64:67], v114 offset:50688
	ds_read_b128 v[60:63], v167 offset:30208
	ds_read2st64_b32 v[216:217], v115 offset0:10 offset1:11
	s_waitcnt lgkmcnt(7)
	v_dot2_f32_f16 v151, v127, v134, 0
	v_dot2_f32_f16 v151, v126, v135, v151
	v_dot2_f32_f16 v151, v125, v136, v151
	v_dot2_f32_f16 v151, v124, v137, v151
	v_dot2_f32_f16 v157, v127, v56, 0
	v_dot2_f32_f16 v157, v126, v57, v157
	v_dot2_f32_f16 v157, v125, v58, v157
	v_add_f32_dpp v151, v151, v151 quad_perm:[1,0,3,2] row_mask:0xf bank_mask:0xf bound_ctrl:1
	v_dot2_f32_f16 v157, v124, v59, v157
	v_pk_mul_f16 v153, v215, v142
	v_add_f32_dpp v151, v151, v151 quad_perm:[2,3,0,1] row_mask:0xf bank_mask:0xf bound_ctrl:1
	v_pk_mul_f16 v154, v215, v143
	v_pk_mul_f16 v155, v215, v144
	v_pk_mul_f16 v156, v215, v145
	v_add_f32_dpp v151, v151, v151 row_half_mirror row_mask:0xf bank_mask:0xf bound_ctrl:1
	v_cvt_pkrtz_f16_f32 v152, -v151, -v151
	ds_read_b128 v[56:59], v114 offset:54784
	v_pk_fma_f16 v153, v152, v138, v153
	v_pk_fma_f16 v154, v152, v139, v154
	v_pk_fma_f16 v155, v152, v140, v155
	v_pk_fma_f16 v156, v152, v141, v156
	v_pk_fma_f16 v127, v127, v130, v153
	v_pk_fma_f16 v126, v126, v131, v154
	v_pk_fma_f16 v125, v125, v132, v155
	v_pk_fma_f16 v124, v124, v133, v156
	ds_read_b128 v[134:137], v114 offset:42624
	ds_read_b128 v[138:141], v114 offset:46720
	ds_read_b128 v[142:145], v114 offset:50816
	ds_read_b128 v[130:133], v167 offset:30336
	s_waitcnt lgkmcnt(5)
	v_dot2_f32_f16 v151, v127, v72, 0
	v_dot2_f32_f16 v151, v126, v73, v151
	v_dot2_f32_f16 v151, v125, v74, v151
	v_dot2_f32_f16 v151, v124, v75, v151
	v_dot2_f32_f16 v158, v127, v146, 0
	v_dot2_f32_f16 v158, v126, v147, v158
	v_dot2_f32_f16 v158, v125, v148, v158
	v_add_f32_dpp v151, v151, v151 quad_perm:[1,0,3,2] row_mask:0xf bank_mask:0xf bound_ctrl:1
	v_dot2_f32_f16 v158, v124, v149, v158
	v_pk_mul_f16 v153, v216, v64
	v_add_f32_dpp v151, v151, v151 quad_perm:[2,3,0,1] row_mask:0xf bank_mask:0xf bound_ctrl:1
	v_pk_mul_f16 v154, v216, v65
	v_pk_mul_f16 v155, v216, v66
	v_pk_mul_f16 v156, v216, v67
	v_add_f32_dpp v151, v151, v151 row_half_mirror row_mask:0xf bank_mask:0xf bound_ctrl:1
	v_cvt_pkrtz_f16_f32 v152, -v151, -v151
	ds_read_b128 v[146:149], v114 offset:54912
	ds_write2st64_b32 v116, v157, v158 offset0:64 offset1:72
	v_pk_fma_f16 v153, v152, v68, v153
	v_pk_fma_f16 v154, v152, v69, v154
	v_pk_fma_f16 v155, v152, v70, v155
	v_pk_fma_f16 v156, v152, v71, v156
	v_pk_fma_f16 v127, v127, v60, v153
	v_pk_fma_f16 v126, v126, v61, v154
	v_pk_fma_f16 v125, v125, v62, v155
	v_pk_fma_f16 v124, v124, v63, v156
	ds_read_b128 v[72:75], v114 offset:42752
	ds_read_b128 v[68:71], v114 offset:46848
	ds_read_b128 v[64:67], v114 offset:50944
	ds_read_b128 v[60:63], v167 offset:30464
	ds_read2st64_b32 v[214:215], v115 offset0:12 offset1:13
	s_waitcnt lgkmcnt(7)
	v_dot2_f32_f16 v151, v127, v134, 0
	v_dot2_f32_f16 v151, v126, v135, v151
	v_dot2_f32_f16 v151, v125, v136, v151
	v_dot2_f32_f16 v151, v124, v137, v151
	v_dot2_f32_f16 v157, v127, v56, 0
	v_dot2_f32_f16 v157, v126, v57, v157
	v_dot2_f32_f16 v157, v125, v58, v157
	v_add_f32_dpp v151, v151, v151 quad_perm:[1,0,3,2] row_mask:0xf bank_mask:0xf bound_ctrl:1
	v_dot2_f32_f16 v157, v124, v59, v157
	v_pk_mul_f16 v153, v217, v142
	v_add_f32_dpp v151, v151, v151 quad_perm:[2,3,0,1] row_mask:0xf bank_mask:0xf bound_ctrl:1
	v_pk_mul_f16 v154, v217, v143
	v_pk_mul_f16 v155, v217, v144
	v_pk_mul_f16 v156, v217, v145
	v_add_f32_dpp v151, v151, v151 row_half_mirror row_mask:0xf bank_mask:0xf bound_ctrl:1
	v_cvt_pkrtz_f16_f32 v152, -v151, -v151
	ds_read_b128 v[56:59], v114 offset:55040
	v_pk_fma_f16 v153, v152, v138, v153
	v_pk_fma_f16 v154, v152, v139, v154
	v_pk_fma_f16 v155, v152, v140, v155
	v_pk_fma_f16 v156, v152, v141, v156
	v_pk_fma_f16 v127, v127, v130, v153
	v_pk_fma_f16 v126, v126, v131, v154
	v_pk_fma_f16 v125, v125, v132, v155
	v_pk_fma_f16 v124, v124, v133, v156
	ds_read_b128 v[134:137], v114 offset:42880
	ds_read_b128 v[138:141], v114 offset:46976
	ds_read_b128 v[142:145], v114 offset:51072
	ds_read_b128 v[130:133], v167 offset:30592
	s_waitcnt lgkmcnt(5)
	v_dot2_f32_f16 v151, v127, v72, 0
	v_dot2_f32_f16 v151, v126, v73, v151
	v_dot2_f32_f16 v151, v125, v74, v151
	v_dot2_f32_f16 v151, v124, v75, v151
	v_dot2_f32_f16 v158, v127, v146, 0
	v_dot2_f32_f16 v158, v126, v147, v158
	v_dot2_f32_f16 v158, v125, v148, v158
	v_add_f32_dpp v151, v151, v151 quad_perm:[1,0,3,2] row_mask:0xf bank_mask:0xf bound_ctrl:1
	v_dot2_f32_f16 v158, v124, v149, v158
	v_pk_mul_f16 v153, v214, v64
	v_add_f32_dpp v151, v151, v151 quad_perm:[2,3,0,1] row_mask:0xf bank_mask:0xf bound_ctrl:1
	v_pk_mul_f16 v154, v214, v65
	v_pk_mul_f16 v155, v214, v66
	v_pk_mul_f16 v156, v214, v67
	v_add_f32_dpp v151, v151, v151 row_half_mirror row_mask:0xf bank_mask:0xf bound_ctrl:1
	v_cvt_pkrtz_f16_f32 v152, -v151, -v151
	ds_read_b128 v[146:149], v114 offset:55168
	ds_write2st64_b32 v116, v157, v158 offset0:80 offset1:88
	v_pk_fma_f16 v153, v152, v68, v153
	v_pk_fma_f16 v154, v152, v69, v154
	v_pk_fma_f16 v155, v152, v70, v155
	v_pk_fma_f16 v156, v152, v71, v156
	v_pk_fma_f16 v127, v127, v60, v153
	v_pk_fma_f16 v126, v126, v61, v154
	v_pk_fma_f16 v125, v125, v62, v155
	v_pk_fma_f16 v124, v124, v63, v156
	ds_read_b128 v[72:75], v114 offset:43008
	ds_read_b128 v[68:71], v114 offset:47104
	ds_read_b128 v[64:67], v114 offset:51200
	ds_read_b128 v[60:63], v167 offset:30720
	ds_read2st64_b32 v[216:217], v115 offset0:14 offset1:15
	s_waitcnt lgkmcnt(7)
	v_dot2_f32_f16 v151, v127, v134, 0
	v_dot2_f32_f16 v151, v126, v135, v151
	v_dot2_f32_f16 v151, v125, v136, v151
	v_dot2_f32_f16 v151, v124, v137, v151
	v_dot2_f32_f16 v157, v127, v56, 0
	v_dot2_f32_f16 v157, v126, v57, v157
	v_dot2_f32_f16 v157, v125, v58, v157
	v_add_f32_dpp v151, v151, v151 quad_perm:[1,0,3,2] row_mask:0xf bank_mask:0xf bound_ctrl:1
	v_dot2_f32_f16 v157, v124, v59, v157
	v_pk_mul_f16 v153, v215, v142
	v_add_f32_dpp v151, v151, v151 quad_perm:[2,3,0,1] row_mask:0xf bank_mask:0xf bound_ctrl:1
	v_pk_mul_f16 v154, v215, v143
	v_pk_mul_f16 v155, v215, v144
	v_pk_mul_f16 v156, v215, v145
	v_add_f32_dpp v151, v151, v151 row_half_mirror row_mask:0xf bank_mask:0xf bound_ctrl:1
	v_cvt_pkrtz_f16_f32 v152, -v151, -v151
	ds_read_b128 v[56:59], v114 offset:55296
	v_pk_fma_f16 v153, v152, v138, v153
	v_pk_fma_f16 v154, v152, v139, v154
	v_pk_fma_f16 v155, v152, v140, v155
	v_pk_fma_f16 v156, v152, v141, v156
	v_pk_fma_f16 v127, v127, v130, v153
	v_pk_fma_f16 v126, v126, v131, v154
	v_pk_fma_f16 v125, v125, v132, v155
	v_pk_fma_f16 v124, v124, v133, v156
	ds_read_b128 v[134:137], v114 offset:43136
	ds_read_b128 v[138:141], v114 offset:47232
	ds_read_b128 v[142:145], v114 offset:51328
	ds_read_b128 v[130:133], v167 offset:30848
	s_waitcnt lgkmcnt(5)
	v_dot2_f32_f16 v151, v127, v72, 0
	v_dot2_f32_f16 v151, v126, v73, v151
	v_dot2_f32_f16 v151, v125, v74, v151
	v_dot2_f32_f16 v151, v124, v75, v151
	v_dot2_f32_f16 v158, v127, v146, 0
	v_dot2_f32_f16 v158, v126, v147, v158
	v_dot2_f32_f16 v158, v125, v148, v158
	v_add_f32_dpp v151, v151, v151 quad_perm:[1,0,3,2] row_mask:0xf bank_mask:0xf bound_ctrl:1
	v_dot2_f32_f16 v158, v124, v149, v158
	v_pk_mul_f16 v153, v216, v64
	v_add_f32_dpp v151, v151, v151 quad_perm:[2,3,0,1] row_mask:0xf bank_mask:0xf bound_ctrl:1
	v_pk_mul_f16 v154, v216, v65
	v_pk_mul_f16 v155, v216, v66
	v_pk_mul_f16 v156, v216, v67
	v_add_f32_dpp v151, v151, v151 row_half_mirror row_mask:0xf bank_mask:0xf bound_ctrl:1
	v_cvt_pkrtz_f16_f32 v152, -v151, -v151
	ds_read_b128 v[146:149], v114 offset:55424
	ds_write2st64_b32 v116, v157, v158 offset0:96 offset1:104
	v_pk_fma_f16 v153, v152, v68, v153
	v_pk_fma_f16 v154, v152, v69, v154
	v_pk_fma_f16 v155, v152, v70, v155
	v_pk_fma_f16 v156, v152, v71, v156
	v_pk_fma_f16 v127, v127, v60, v153
	v_pk_fma_f16 v126, v126, v61, v154
	v_pk_fma_f16 v125, v125, v62, v155
	v_pk_fma_f16 v124, v124, v63, v156
	s_waitcnt lgkmcnt(0)
	v_dot2_f32_f16 v151, v127, v134, 0
	v_dot2_f32_f16 v151, v126, v135, v151
	v_dot2_f32_f16 v151, v125, v136, v151
	v_dot2_f32_f16 v151, v124, v137, v151
	v_dot2_f32_f16 v157, v127, v56, 0
	v_dot2_f32_f16 v157, v126, v57, v157
	v_dot2_f32_f16 v157, v125, v58, v157
	v_add_f32_dpp v151, v151, v151 quad_perm:[1,0,3,2] row_mask:0xf bank_mask:0xf bound_ctrl:1
	v_dot2_f32_f16 v157, v124, v59, v157
	v_pk_mul_f16 v153, v217, v142
	v_add_f32_dpp v151, v151, v151 quad_perm:[2,3,0,1] row_mask:0xf bank_mask:0xf bound_ctrl:1
	v_pk_mul_f16 v154, v217, v143
	v_pk_mul_f16 v155, v217, v144
	v_pk_mul_f16 v156, v217, v145
	v_add_f32_dpp v151, v151, v151 row_half_mirror row_mask:0xf bank_mask:0xf bound_ctrl:1
	v_cvt_pkrtz_f16_f32 v152, -v151, -v151
	v_pk_fma_f16 v153, v152, v138, v153
	v_pk_fma_f16 v154, v152, v139, v154
	v_pk_fma_f16 v155, v152, v140, v155
	v_pk_fma_f16 v156, v152, v141, v156
	v_pk_fma_f16 v127, v127, v130, v153
	v_pk_fma_f16 v126, v126, v131, v154
	v_pk_fma_f16 v125, v125, v132, v155
	v_pk_fma_f16 v124, v124, v133, v156
	v_dot2_f32_f16 v158, v127, v146, 0
	v_dot2_f32_f16 v158, v126, v147, v158
	v_dot2_f32_f16 v158, v125, v148, v158
	v_dot2_f32_f16 v158, v124, v149, v158
	s_nop 2
	ds_write2st64_b32 v116, v157, v158 offset0:112 offset1:120
	s_xor_b32 s100, s100, 0xe100
	s_cmpk_lg_i32 s30, 0x80
	s_cbranch_scc0 .LBB0_1250
	s_mov_b32 s4, s30
	s_and_saveexec_b64 s[18:19], s[10:11]
	s_cbranch_execnz .LBB0_1229
	s_branch .LBB0_1230
